# S5 chunk states Z kept on-chip: P1 GEMM epilogue global stores removed, accumulators written straight to LDS and scanned there (no Z round trip through memory); plus earlier prep/x-rows/final-norm edi
# speedup vs baseline: 1.0092x; 1.0092x over previous
; #define PG8_STAGE(bufoff, gbase, voff) do { _Pragma("unroll") for (int _i = 0; _i < 2; ++_i) \
;         __builtin_amdgcn_global_load_lds((const unsigned*)((const char*)(gbase) + (voff)[_i]), (LAS unsigned*)(lds + (bufoff) + ldsw + _i * 8192), 16, 0, 0); } while (0)
; #define PG8_LDA(dst, b, h) do { _Pragma("unroll") for (int m = 0; m < 4; ++m) _Pragma("unroll") for (int k = 0; k < 2; ++k) dst[m][k] = *(const LAS bf16x8*)(lds + PG8_SA(b, h) + aoff + m * 2048 + k * 1024); } while (0)
; #define PG8_WAIT_V(n) asm volatile("s_waitcnt vmcnt(" #n ")" ::: "memory")
; #define PG8_WAIT_L(n) asm volatile("s_waitcnt lgkmcnt(" #n ")" ::: "memory")
; template <class Epi, class Sched>
; __device__ __forceinline__ void gemm_phase(LAS unsigned char* lds, const Gemm g, const Sched& S, const Epi& E) {
;     ...
;         for (int t = 0; t < nt; t += 2) {
;             const bool last = (t == nt - 2);
;             const char* a1 = cA + (size_t)(t + 1) * kstep;
;             const char* a2 = last ? nA : cA + (size_t)(t + 2) * kstep; const char* b2 = last ? nB : cB + (size_t)(t + 2) * kstep;
;             const char* a3 = a2 + kstep; const char* b3 = b2 + kstep;
;             PG8_LDB(B0, 0, 0); PG8_SCHED; PG8_LDA(At, 0, 0); PG8_STAGE(PG8_SA(1, 1), a1 + hstepA, voffA);
;             PG8_WAIT_L(8); PG8_BAR; PG8_WAIT_L(0); PG8_MMA(0, 0, At, B0); PG8_BAR; PG8_SCHED;
;             PG8_LDB(B1, 0, 1); PG8_STAGE(PG8_SB(0, 0), b2, voffB);
;             PG8_BAR; PG8_WAIT_L(0); PG8_MMA(0, 1, At, B1); PG8_BAR;
;             PG8_LDA(At, 0, 1); PG8_STAGE(PG8_SA(0, 0), a2, voffA);
;             PG8_BAR; PG8_WAIT_L(0); PG8_MMA(1, 0, At, B0); PG8_BAR; PG8_SCHED;
;             PG8_STAGE(PG8_SB(0, 1), b2 + hstepB, voffB);
;             PG8_WAIT_V(6); PG8_BAR; PG8_MMA(1, 1, At, B1); PG8_BAR;
;             PG8_LDB(B0, 1, 0); PG8_SCHED; PG8_LDA(At, 1, 0); PG8_STAGE(PG8_SA(0, 1), a2 + hstepA, voffA);
;             PG8_WAIT_L(8); PG8_BAR; PG8_WAIT_L(0); PG8_MMA(0, 0, At, B0); PG8_BAR; PG8_SCHED;
;             PG8_LDB(B1, 1, 1); PG8_STAGE(PG8_SB(1, 0), b3, voffB);
;             PG8_BAR; PG8_WAIT_L(0); PG8_MMA(0, 1, At, B1); PG8_BAR;
;             PG8_LDA(At, 1, 1); PG8_STAGE(PG8_SA(1, 0), a3, voffA);
;             PG8_BAR; PG8_WAIT_L(0); PG8_MMA(1, 0, At, B0); PG8_BAR; PG8_SCHED;
;             PG8_STAGE(PG8_SB(1, 1), b3 + hstepB, voffB);
;             PG8_WAIT_V(6); PG8_BAR; PG8_MMA(1, 1, At, B1); PG8_BAR;
.LBB0_580:
	s_add_u32 s42, s40, 0x100
	s_addc_u32 s43, s41, 0
	s_add_i32 s24, 0, 0x10000
	v_add_u32_e32 v162, s24, v144
	ds_read_b128 v[146:149], v162
	ds_read_b128 v[150:153], v162 offset:1024
	ds_read_b128 v[170:173], v162 offset:2048
	ds_read_b128 v[174:177], v162 offset:3072
	s_cmp_eq_u32 s58, 4
	s_cselect_b32 s47, s1, s43
	s_cselect_b32 s46, s0, s42
	s_cselect_b32 s45, s54, s57
	s_cselect_b32 s44, s55, s56
	v_lshl_add_u64 v[198:199], s[40:41], 0, v[140:141]
	s_add_i32 m0, s28, 0xc000
	ds_read_b128 v[178:181], v145
	ds_read_b128 v[182:185], v145 offset:1024
	ds_read_b128 v[186:189], v145 offset:2048
	ds_read_b128 v[190:193], v145 offset:3072
	ds_read_b128 v[194:197], v145 offset:4096
	ds_read_b128 v[210:213], v145 offset:5120
	ds_read_b128 v[214:217], v145 offset:6144
	ds_read_b128 v[218:221], v145 offset:7168
	global_load_lds_dwordx4 v[198:199], off
	v_lshl_add_u64 v[198:199], s[40:41], 0, v[142:143]
	s_add_i32 m0, s28, 0xe000
	s_nop 0
	global_load_lds_dwordx4 v[198:199], off
	s_waitcnt lgkmcnt(8)
	s_barrier
	s_waitcnt lgkmcnt(0)
	s_setprio 1
	s_waitcnt lgkmcnt(0)
	v_mfma_f32_16x16x32_bf16 v[126:129], v[146:149], v[178:181], v[126:129]
	v_mfma_f32_16x16x32_bf16 v[122:125], v[170:173], v[178:181], v[122:125]
	v_mfma_f32_16x16x32_bf16 v[118:121], v[146:149], v[186:189], v[118:121]
	v_mfma_f32_16x16x32_bf16 v[114:117], v[170:173], v[186:189], v[114:117]
	v_mfma_f32_16x16x32_bf16 v[106:109], v[146:149], v[194:197], v[106:109]
	v_mfma_f32_16x16x32_bf16 v[98:101], v[170:173], v[194:197], v[98:101]
	v_mfma_f32_16x16x32_bf16 v[90:93], v[146:149], v[214:217], v[90:93]
	v_mfma_f32_16x16x32_bf16 v[82:85], v[170:173], v[214:217], v[82:85]
	v_mfma_f32_16x16x32_bf16 v[126:129], v[150:153], v[182:185], v[126:129]
	v_mfma_f32_16x16x32_bf16 v[122:125], v[174:177], v[182:185], v[122:125]
	v_mfma_f32_16x16x32_bf16 v[118:121], v[150:153], v[190:193], v[118:121]
	v_mfma_f32_16x16x32_bf16 v[114:117], v[174:177], v[190:193], v[114:117]
	v_mfma_f32_16x16x32_bf16 v[106:109], v[150:153], v[210:213], v[106:109]
	v_mfma_f32_16x16x32_bf16 v[98:101], v[174:177], v[210:213], v[98:101]
	v_mfma_f32_16x16x32_bf16 v[90:93], v[150:153], v[218:221], v[90:93]
	v_mfma_f32_16x16x32_bf16 v[82:85], v[174:177], v[218:221], v[82:85]
	s_setprio 0
	s_barrier
	s_add_i32 s25, 0, 0x14000
	s_add_i32 s23, s24, s26
	v_add_u32_e32 v162, s25, v144
	v_lshl_add_u64 v[198:199], s[44:45], 0, v[134:135]
	s_mov_b32 m0, s23
	ds_read_b128 v[222:225], v162
	ds_read_b128 v[226:229], v162 offset:1024
	ds_read_b128 v[230:233], v162 offset:2048
	ds_read_b128 v[234:237], v162 offset:3072
	global_load_lds_dwordx4 v[198:199], off
	v_lshl_add_u64 v[238:239], s[44:45], 0, v[130:131]
	s_add_i32 m0, s23, 0x2000
	s_nop 0
	global_load_lds_dwordx4 v[238:239], off
	s_barrier
	s_waitcnt lgkmcnt(0)
	s_setprio 1
	s_waitcnt lgkmcnt(0)
	v_mfma_f32_16x16x32_bf16 v[110:113], v[222:225], v[178:181], v[110:113]
	v_mfma_f32_16x16x32_bf16 v[102:105], v[230:233], v[178:181], v[102:105]
	v_mfma_f32_16x16x32_bf16 v[94:97], v[222:225], v[186:189], v[94:97]
	v_mfma_f32_16x16x32_bf16 v[86:89], v[230:233], v[186:189], v[86:89]
	v_mfma_f32_16x16x32_bf16 v[78:81], v[222:225], v[194:197], v[78:81]
	v_mfma_f32_16x16x32_bf16 v[74:77], v[230:233], v[194:197], v[74:77]
	v_mfma_f32_16x16x32_bf16 v[70:73], v[222:225], v[214:217], v[70:73]
	v_mfma_f32_16x16x32_bf16 v[66:69], v[230:233], v[214:217], v[66:69]
	v_mfma_f32_16x16x32_bf16 v[110:113], v[226:229], v[182:185], v[110:113]
	v_mfma_f32_16x16x32_bf16 v[102:105], v[234:237], v[182:185], v[102:105]
	v_mfma_f32_16x16x32_bf16 v[94:97], v[226:229], v[190:193], v[94:97]
	v_mfma_f32_16x16x32_bf16 v[86:89], v[234:237], v[190:193], v[86:89]
	v_mfma_f32_16x16x32_bf16 v[78:81], v[226:229], v[210:213], v[78:81]
	v_mfma_f32_16x16x32_bf16 v[74:77], v[234:237], v[210:213], v[74:77]
	v_mfma_f32_16x16x32_bf16 v[70:73], v[226:229], v[218:221], v[70:73]
	v_mfma_f32_16x16x32_bf16 v[66:69], v[234:237], v[218:221], v[66:69]
	s_setprio 0
	s_mov_b32 m0, s28
	v_lshl_add_u64 v[240:241], s[46:47], 0, v[136:137]
	s_barrier
	ds_read_b128 v[178:181], v145 offset:16384
	ds_read_b128 v[182:185], v145 offset:17408
	ds_read_b128 v[186:189], v145 offset:18432
	ds_read_b128 v[190:193], v145 offset:19456
	ds_read_b128 v[194:197], v145 offset:20480
	ds_read_b128 v[210:213], v145 offset:21504
	ds_read_b128 v[214:217], v145 offset:22528
	ds_read_b128 v[218:221], v145 offset:23552
	global_load_lds_dwordx4 v[240:241], off
	v_lshl_add_u64 v[242:243], s[46:47], 0, v[132:133]
	s_mov_b32 m0, s29
	s_nop 0
	global_load_lds_dwordx4 v[242:243], off
	s_barrier
	s_waitcnt lgkmcnt(0)
	s_setprio 1
	s_waitcnt lgkmcnt(0)
	v_mfma_f32_16x16x32_bf16 v[62:65], v[146:149], v[178:181], v[62:65]
	v_mfma_f32_16x16x32_bf16 v[58:61], v[170:173], v[178:181], v[58:61]
	v_mfma_f32_16x16x32_bf16 v[54:57], v[146:149], v[186:189], v[54:57]
	v_mfma_f32_16x16x32_bf16 v[50:53], v[170:173], v[186:189], v[50:53]
	v_mfma_f32_16x16x32_bf16 v[38:41], v[146:149], v[194:197], v[38:41]
	v_mfma_f32_16x16x32_bf16 v[34:37], v[170:173], v[194:197], v[34:37]
	v_mfma_f32_16x16x32_bf16 v[22:25], v[146:149], v[214:217], v[22:25]
	v_mfma_f32_16x16x32_bf16 v[18:21], v[170:173], v[214:217], v[18:21]
	v_mfma_f32_16x16x32_bf16 v[62:65], v[150:153], v[182:185], v[62:65]
	v_mfma_f32_16x16x32_bf16 v[58:61], v[174:177], v[182:185], v[58:61]
	v_mfma_f32_16x16x32_bf16 v[54:57], v[150:153], v[190:193], v[54:57]
	v_mfma_f32_16x16x32_bf16 v[50:53], v[174:177], v[190:193], v[50:53]
	v_mfma_f32_16x16x32_bf16 v[38:41], v[150:153], v[210:213], v[38:41]
	v_mfma_f32_16x16x32_bf16 v[34:37], v[174:177], v[210:213], v[34:37]
	v_mfma_f32_16x16x32_bf16 v[22:25], v[150:153], v[218:221], v[22:25]
	v_mfma_f32_16x16x32_bf16 v[18:21], v[174:177], v[218:221], v[18:21]
	s_setprio 0
	s_barrier
; #define PG8_STAGE(bufoff, gbase, voff) do { _Pragma("unroll") for (int _i = 0; _i < 2; ++_i) \
;         __builtin_amdgcn_global_load_lds((const unsigned*)((const char*)(gbase) + (voff)[_i]), (LAS unsigned*)(lds + (bufoff) + ldsw + _i * 8192), 16, 0, 0); } while (0)
; #define PG8_LDA(dst, b, h) do { _Pragma("unroll") for (int m = 0; m < 4; ++m) _Pragma("unroll") for (int k = 0; k < 2; ++k) dst[m][k] = *(const LAS bf16x8*)(lds + PG8_SA(b, h) + aoff + m * 2048 + k * 1024); } while (0)
; #define PG8_WAIT_V(n) asm volatile("s_waitcnt vmcnt(" #n ")" ::: "memory")
; #define PG8_WAIT_L(n) asm volatile("s_waitcnt lgkmcnt(" #n ")" ::: "memory")
; template <class Epi, class Sched>
; __device__ __forceinline__ void gemm_phase(LAS unsigned char* lds, const Gemm g, const Sched& S, const Epi& E) {
;     ...
;         for (int t = 0; t < nt; t += 2) {
;             const bool last = (t == nt - 2);
;             const char* a1 = cA + (size_t)(t + 1) * kstep;
;             const char* a2 = last ? nA : cA + (size_t)(t + 2) * kstep; const char* b2 = last ? nB : cB + (size_t)(t + 2) * kstep;
;             const char* a3 = a2 + kstep; const char* b3 = b2 + kstep;
;             PG8_LDB(B0, 0, 0); PG8_SCHED; PG8_LDA(At, 0, 0); PG8_STAGE(PG8_SA(1, 1), a1 + hstepA, voffA);
;             PG8_WAIT_L(8); PG8_BAR; PG8_WAIT_L(0); PG8_MMA(0, 0, At, B0); PG8_BAR; PG8_SCHED;
;             PG8_LDB(B1, 0, 1); PG8_STAGE(PG8_SB(0, 0), b2, voffB);
;             PG8_BAR; PG8_WAIT_L(0); PG8_MMA(0, 1, At, B1); PG8_BAR;
;             PG8_LDA(At, 0, 1); PG8_STAGE(PG8_SA(0, 0), a2, voffA);
;             PG8_BAR; PG8_WAIT_L(0); PG8_MMA(1, 0, At, B0); PG8_BAR; PG8_SCHED;
;             PG8_STAGE(PG8_SB(0, 1), b2 + hstepB, voffB);
;             PG8_WAIT_V(6); PG8_BAR; PG8_MMA(1, 1, At, B1); PG8_BAR;
;             PG8_LDB(B0, 1, 0); PG8_SCHED; PG8_LDA(At, 1, 0); PG8_STAGE(PG8_SA(0, 1), a2 + hstepA, voffA);
;             PG8_WAIT_L(8); PG8_BAR; PG8_WAIT_L(0); PG8_MMA(0, 0, At, B0); PG8_BAR; PG8_SCHED;
;             PG8_LDB(B1, 1, 1); PG8_STAGE(PG8_SB(1, 0), b3, voffB);
;             PG8_BAR; PG8_WAIT_L(0); PG8_MMA(0, 1, At, B1); PG8_BAR;
;             PG8_LDA(At, 1, 1); PG8_STAGE(PG8_SA(1, 0), a3, voffA);
;             PG8_BAR; PG8_WAIT_L(0); PG8_MMA(1, 0, At, B0); PG8_BAR; PG8_SCHED;
;             PG8_STAGE(PG8_SB(1, 1), b3 + hstepB, voffB);
;             PG8_WAIT_V(6); PG8_BAR; PG8_MMA(1, 1, At, B1); PG8_BAR;
	s_add_u32 s40, s44, 0x20000
	s_addc_u32 s41, s45, 0
	s_add_i32 s23, s25, s26
	v_lshl_add_u64 v[146:147], s[40:41], 0, v[134:135]
	s_mov_b32 m0, s23
	s_nop 0
	global_load_lds_dwordx4 v[146:147], off
	v_lshl_add_u64 v[146:147], s[40:41], 0, v[130:131]
	s_add_i32 m0, s23, 0x2000
	s_nop 0
	global_load_lds_dwordx4 v[146:147], off
	s_waitcnt vmcnt(6)
	s_barrier
	s_setprio 1
	v_mfma_f32_16x16x32_bf16 v[46:49], v[222:225], v[178:181], v[46:49]
	v_mfma_f32_16x16x32_bf16 v[42:45], v[230:233], v[178:181], v[42:45]
	v_mfma_f32_16x16x32_bf16 v[30:33], v[222:225], v[186:189], v[30:33]
	v_mfma_f32_16x16x32_bf16 v[26:29], v[230:233], v[186:189], v[26:29]
	v_mfma_f32_16x16x32_bf16 v[14:17], v[222:225], v[194:197], v[14:17]
	v_mfma_f32_16x16x32_bf16 v[10:13], v[230:233], v[194:197], v[10:13]
	v_mfma_f32_16x16x32_bf16 v[6:9], v[222:225], v[214:217], v[6:9]
	v_mfma_f32_16x16x32_bf16 v[2:5], v[230:233], v[214:217], v[2:5]
	v_mfma_f32_16x16x32_bf16 v[46:49], v[226:229], v[182:185], v[46:49]
	v_mfma_f32_16x16x32_bf16 v[42:45], v[234:237], v[182:185], v[42:45]
	v_mfma_f32_16x16x32_bf16 v[30:33], v[226:229], v[190:193], v[30:33]
	v_mfma_f32_16x16x32_bf16 v[26:29], v[234:237], v[190:193], v[26:29]
	v_mfma_f32_16x16x32_bf16 v[14:17], v[226:229], v[210:213], v[14:17]
	v_mfma_f32_16x16x32_bf16 v[10:13], v[234:237], v[210:213], v[10:13]
	v_mfma_f32_16x16x32_bf16 v[6:9], v[226:229], v[218:221], v[6:9]
	v_mfma_f32_16x16x32_bf16 v[2:5], v[234:237], v[218:221], v[2:5]
	s_setprio 0
	s_add_i32 s27, 0, 0x18000
	v_add_u32_e32 v162, s27, v144
	s_barrier
	ds_read_b128 v[146:149], v162
	ds_read_b128 v[150:153], v162 offset:1024
	ds_read_b128 v[170:173], v162 offset:2048
	ds_read_b128 v[174:177], v162 offset:3072
	s_add_u32 s40, s46, 0x30000
	s_addc_u32 s41, s47, 0
	s_mov_b32 m0, s35
	v_lshl_add_u64 v[222:223], s[40:41], 0, v[136:137]
	ds_read_b128 v[178:181], v145 offset:32768
	ds_read_b128 v[182:185], v145 offset:33792
	ds_read_b128 v[186:189], v145 offset:34816
	ds_read_b128 v[190:193], v145 offset:35840
	ds_read_b128 v[194:197], v145 offset:36864
	ds_read_b128 v[210:213], v145 offset:37888
	ds_read_b128 v[214:217], v145 offset:38912
	ds_read_b128 v[218:221], v145 offset:39936
	global_load_lds_dwordx4 v[222:223], off
	v_lshl_add_u64 v[222:223], s[40:41], 0, v[132:133]
	s_mov_b32 m0, s48
	s_nop 0
	global_load_lds_dwordx4 v[222:223], off
	s_waitcnt lgkmcnt(8)
	s_barrier
	s_waitcnt lgkmcnt(0)
	s_setprio 1
	s_waitcnt lgkmcnt(0)
	v_mfma_f32_16x16x32_bf16 v[126:129], v[146:149], v[178:181], v[126:129]
	v_mfma_f32_16x16x32_bf16 v[122:125], v[170:173], v[178:181], v[122:125]
	v_mfma_f32_16x16x32_bf16 v[118:121], v[146:149], v[186:189], v[118:121]
	v_mfma_f32_16x16x32_bf16 v[114:117], v[170:173], v[186:189], v[114:117]
	v_mfma_f32_16x16x32_bf16 v[106:109], v[146:149], v[194:197], v[106:109]
	v_mfma_f32_16x16x32_bf16 v[98:101], v[170:173], v[194:197], v[98:101]
	v_mfma_f32_16x16x32_bf16 v[90:93], v[146:149], v[214:217], v[90:93]
	v_mfma_f32_16x16x32_bf16 v[82:85], v[170:173], v[214:217], v[82:85]
	v_mfma_f32_16x16x32_bf16 v[126:129], v[150:153], v[182:185], v[126:129]
	v_mfma_f32_16x16x32_bf16 v[122:125], v[174:177], v[182:185], v[122:125]
	v_mfma_f32_16x16x32_bf16 v[118:121], v[150:153], v[190:193], v[118:121]
	v_mfma_f32_16x16x32_bf16 v[114:117], v[174:177], v[190:193], v[114:117]
	v_mfma_f32_16x16x32_bf16 v[106:109], v[150:153], v[210:213], v[106:109]
	v_mfma_f32_16x16x32_bf16 v[98:101], v[174:177], v[210:213], v[98:101]
	v_mfma_f32_16x16x32_bf16 v[90:93], v[150:153], v[218:221], v[90:93]
	v_mfma_f32_16x16x32_bf16 v[82:85], v[174:177], v[218:221], v[82:85]
	s_setprio 0
	s_barrier
	s_add_i32 s31, 0, 0x1c000
	s_add_i32 s23, s27, s26
	v_add_u32_e32 v162, s31, v144
	v_lshl_add_u64 v[198:199], v[198:199], 0, s[10:11]
	s_mov_b32 m0, s23
	ds_read_b128 v[222:225], v162
	ds_read_b128 v[226:229], v162 offset:1024
	ds_read_b128 v[230:233], v162 offset:2048
	ds_read_b128 v[234:237], v162 offset:3072
	global_load_lds_dwordx4 v[198:199], off
	v_lshl_add_u64 v[198:199], v[238:239], 0, s[10:11]
	s_add_i32 m0, s23, 0x2000
	s_nop 0
	global_load_lds_dwordx4 v[198:199], off
	s_barrier
	s_waitcnt lgkmcnt(0)
	s_setprio 1
	s_waitcnt lgkmcnt(0)
	v_mfma_f32_16x16x32_bf16 v[110:113], v[222:225], v[178:181], v[110:113]
	v_mfma_f32_16x16x32_bf16 v[102:105], v[230:233], v[178:181], v[102:105]
	v_mfma_f32_16x16x32_bf16 v[94:97], v[222:225], v[186:189], v[94:97]
	v_mfma_f32_16x16x32_bf16 v[86:89], v[230:233], v[186:189], v[86:89]
	v_mfma_f32_16x16x32_bf16 v[78:81], v[222:225], v[194:197], v[78:81]
	v_mfma_f32_16x16x32_bf16 v[74:77], v[230:233], v[194:197], v[74:77]
	v_mfma_f32_16x16x32_bf16 v[70:73], v[222:225], v[214:217], v[70:73]
	v_mfma_f32_16x16x32_bf16 v[66:69], v[230:233], v[214:217], v[66:69]
	v_mfma_f32_16x16x32_bf16 v[110:113], v[226:229], v[182:185], v[110:113]
	v_mfma_f32_16x16x32_bf16 v[102:105], v[234:237], v[182:185], v[102:105]
	v_mfma_f32_16x16x32_bf16 v[94:97], v[226:229], v[190:193], v[94:97]
	v_mfma_f32_16x16x32_bf16 v[86:89], v[234:237], v[190:193], v[86:89]
	v_mfma_f32_16x16x32_bf16 v[78:81], v[226:229], v[210:213], v[78:81]
	v_mfma_f32_16x16x32_bf16 v[74:77], v[234:237], v[210:213], v[74:77]
	v_mfma_f32_16x16x32_bf16 v[70:73], v[226:229], v[218:221], v[70:73]
	v_mfma_f32_16x16x32_bf16 v[66:69], v[234:237], v[218:221], v[66:69]
	s_setprio 0
	s_mov_b32 m0, s49
	v_lshl_add_u64 v[198:199], v[240:241], 0, s[10:11]
	s_barrier
	ds_read_b128 v[178:181], v145 offset:49152
	ds_read_b128 v[182:185], v145 offset:50176
	ds_read_b128 v[186:189], v145 offset:51200
	ds_read_b128 v[190:193], v145 offset:52224
	ds_read_b128 v[194:197], v145 offset:53248
	ds_read_b128 v[210:213], v145 offset:54272
	ds_read_b128 v[214:217], v145 offset:55296
	ds_read_b128 v[218:221], v145 offset:56320
	global_load_lds_dwordx4 v[198:199], off
	v_lshl_add_u64 v[198:199], v[242:243], 0, s[10:11]
	s_mov_b32 m0, s50
	s_nop 0
	global_load_lds_dwordx4 v[198:199], off
	s_barrier
; #define LAS __attribute__((address_space(3)))
; #define PG8_STAGE(bufoff, gbase, voff) do { _Pragma("unroll") for (int _i = 0; _i < 2; ++_i) \
;         __builtin_amdgcn_global_load_lds((const unsigned*)((const char*)(gbase) + (voff)[_i]), (LAS unsigned*)(lds + (bufoff) + ldsw + _i * 8192), 16, 0, 0); } while (0)
; #define PG8_LDA(dst, b, h) do { _Pragma("unroll") for (int m = 0; m < 4; ++m) _Pragma("unroll") for (int k = 0; k < 2; ++k) dst[m][k] = *(const LAS bf16x8*)(lds + PG8_SA(b, h) + aoff + m * 2048 + k * 1024); } while (0)
; #define PG8_MMA(ai, bj, At, Bt) do { __builtin_amdgcn_s_setprio(1); _Pragma("unroll") for (int m = 0; m < 4; ++m) _Pragma("unroll") for (int n = 0; n < 2; ++n) _Pragma("unroll") for (int k = 0; k < 2; ++k) \
;         acc[ai][bj][m][n] = __builtin_amdgcn_mfma_f32_16x16x32_bf16(Bt[n][k], At[m][k], acc[ai][bj][m][n], 0, 0, 0); __builtin_amdgcn_s_setprio(0); } while (0)
; template <class Epi, class Sched>
; __device__ __forceinline__ void gemm_phase(LAS unsigned char* lds, const Gemm g, const Sched& S, const Epi& E) {
;     ...
;             PG8_BAR; PG8_WAIT_L(0); PG8_MMA(0, 1, At, B1); PG8_BAR;
;             PG8_LDA(At, 1, 1); PG8_STAGE(PG8_SA(1, 0), a3, voffA);
;             PG8_BAR; PG8_WAIT_L(0); PG8_MMA(1, 0, At, B0); PG8_BAR; PG8_SCHED;
;             PG8_STAGE(PG8_SB(1, 1), b3 + hstepB, voffB);
;             PG8_WAIT_V(6); PG8_BAR; PG8_MMA(1, 1, At, B1); PG8_BAR;
;         }
;         E(acc, cur, ui, (const LAS float*)(lds + STAGE_BYTES), wr, wc, fr, fq);
;         if (!has_next) break;
; __device__ __forceinline__ void s5_carry2(const Params& P, int j, int g) {
;     int tid = threadIdx.x; asm volatile("" : "+v"(tid));
;     const int wid = __builtin_amdgcn_readfirstlane(tid >> 6), pp = tid & 63;
;     if (wid < 2) {
;         const int dir = wid; const int idx = ((j * 2 + dir) * 64 + g) * 64 + pp;
;         const f32x2 a32 = *(const f32x2*)(P.ws + WS_A32 + (size_t)idx * 8); const float ar = a32.x, ai = a32.y;
;         const float* zp = (const float*)(P.ws + WS_Z) + (size_t)(g * 256) * 256 + dir * 128 + pp;
;         bf16_t* up = (bf16_t*)(P.ws + WS_U2) + (size_t)g * 256 * 768 + 512 + dir * 128 + pp;
;         float cr = 0.f, cim = 0.f; float zr[8], zi[8], nzr[8], nzi[8];
; #pragma unroll
;         for (int u = 0; u < 8; ++u) { const int n = dir ? (255 - u) : u; zr[u] = zp[(size_t)n * 256]; zi[u] = zp[(size_t)n * 256 + 64]; }
	s_waitcnt lgkmcnt(0)
	s_setprio 1
	s_waitcnt lgkmcnt(0)
	v_mfma_f32_16x16x32_bf16 v[62:65], v[146:149], v[178:181], v[62:65]
	v_mfma_f32_16x16x32_bf16 v[58:61], v[170:173], v[178:181], v[58:61]
	v_mfma_f32_16x16x32_bf16 v[54:57], v[146:149], v[186:189], v[54:57]
	v_mfma_f32_16x16x32_bf16 v[50:53], v[170:173], v[186:189], v[50:53]
	v_mfma_f32_16x16x32_bf16 v[38:41], v[146:149], v[194:197], v[38:41]
	v_mfma_f32_16x16x32_bf16 v[34:37], v[170:173], v[194:197], v[34:37]
	v_mfma_f32_16x16x32_bf16 v[22:25], v[146:149], v[214:217], v[22:25]
	v_mfma_f32_16x16x32_bf16 v[18:21], v[170:173], v[214:217], v[18:21]
	v_mfma_f32_16x16x32_bf16 v[62:65], v[150:153], v[182:185], v[62:65]
	v_mfma_f32_16x16x32_bf16 v[58:61], v[174:177], v[182:185], v[58:61]
	v_mfma_f32_16x16x32_bf16 v[54:57], v[150:153], v[190:193], v[54:57]
	v_mfma_f32_16x16x32_bf16 v[50:53], v[174:177], v[190:193], v[50:53]
	v_mfma_f32_16x16x32_bf16 v[38:41], v[150:153], v[210:213], v[38:41]
	v_mfma_f32_16x16x32_bf16 v[34:37], v[174:177], v[210:213], v[34:37]
	v_mfma_f32_16x16x32_bf16 v[22:25], v[150:153], v[218:221], v[22:25]
	v_mfma_f32_16x16x32_bf16 v[18:21], v[174:177], v[218:221], v[18:21]
	s_setprio 0
	s_barrier
	s_add_u32 s40, s44, 0x20080
	s_addc_u32 s41, s45, 0
	s_add_i32 s23, s31, s26
	v_lshl_add_u64 v[146:147], s[40:41], 0, v[134:135]
	s_mov_b32 m0, s23
	s_nop 0
	global_load_lds_dwordx4 v[146:147], off
	v_lshl_add_u64 v[146:147], s[40:41], 0, v[130:131]
	s_add_i32 m0, s23, 0x2000
	s_nop 0
	global_load_lds_dwordx4 v[146:147], off
	s_waitcnt vmcnt(6)
	s_barrier
	s_setprio 1
	v_mfma_f32_16x16x32_bf16 v[46:49], v[222:225], v[178:181], v[46:49]
	v_mfma_f32_16x16x32_bf16 v[42:45], v[230:233], v[178:181], v[42:45]
	v_mfma_f32_16x16x32_bf16 v[30:33], v[222:225], v[186:189], v[30:33]
	v_mfma_f32_16x16x32_bf16 v[26:29], v[230:233], v[186:189], v[26:29]
	v_mfma_f32_16x16x32_bf16 v[14:17], v[222:225], v[194:197], v[14:17]
	v_mfma_f32_16x16x32_bf16 v[10:13], v[230:233], v[194:197], v[10:13]
	v_mfma_f32_16x16x32_bf16 v[6:9], v[222:225], v[214:217], v[6:9]
	v_mfma_f32_16x16x32_bf16 v[2:5], v[230:233], v[214:217], v[2:5]
	v_mfma_f32_16x16x32_bf16 v[46:49], v[226:229], v[182:185], v[46:49]
	v_mfma_f32_16x16x32_bf16 v[42:45], v[234:237], v[182:185], v[42:45]
	v_mfma_f32_16x16x32_bf16 v[30:33], v[226:229], v[190:193], v[30:33]
	v_mfma_f32_16x16x32_bf16 v[26:29], v[234:237], v[190:193], v[26:29]
	v_mfma_f32_16x16x32_bf16 v[14:17], v[226:229], v[210:213], v[14:17]
	v_mfma_f32_16x16x32_bf16 v[10:13], v[234:237], v[210:213], v[10:13]
	v_mfma_f32_16x16x32_bf16 v[6:9], v[226:229], v[218:221], v[6:9]
	v_mfma_f32_16x16x32_bf16 v[2:5], v[234:237], v[218:221], v[2:5]
	s_setprio 0
	s_add_i32 s58, s58, 2
	s_add_u32 s56, s56, 0x100
	s_addc_u32 s57, s57, 0
	s_cmp_gt_u32 s58, 5
	s_mov_b64 s[40:41], s[42:43]
	s_barrier
	s_cbranch_scc0 .LBB0_580
	s_mov_b32 s23, 0x20000
	s_mov_b64 s[40:41], 0x20000
	s_mov_b32 s53, s52
	s_mov_b32 s46, s52
	s_mov_b64 s[42:43], s[36:37]
	s_nop 0
	s_nop 1
	s_mov_b32 s23, 0x24000
	s_nop 0
	s_mov_b64 s[40:41], 0x24000
	s_nop 0
	s_mov_b32 s23, 0x28000
	s_nop 0
	s_mov_b64 s[40:41], 0x28000
	s_nop 0
	s_nop 0
	s_mov_b64 s[40:41], 0x2c000
	s_nop 0
	s_nop 0
	s_and_b64 vcc, exec, s[20:21]
	s_mov_b64 s[40:41], s[0:1]
	s_cbranch_vccz .LBB0_577
	s_waitcnt vmcnt(0)
	s_cmpk_gt_u32 s34, 0xff
	s_cbranch_scc1 .LBB0_584
	s_barrier
.LBB0_584:
	v_mov_b32_e32 v1, v200
	s_barrier
	s_waitcnt vmcnt(0)
	s_waitcnt vmcnt(0) lgkmcnt(0)
	s_barrier
	buffer_inv sc1
	s_waitcnt vmcnt(0)
	s_nop 0
	v_readfirstlane_b32 s0, v1
	s_ashr_i32 s1, s0, 6
	v_and_b32_e32 v130, 63, v200
	v_and_b32_e32 v131, 15, v130
	v_lshrrev_b32_e32 v132, 4, v130
	s_lshr_b32 s12, s1, 2
	s_and_b32 s13, s1, 3
	s_lshl_b32 s20, s12, 16
	s_lshl_b32 s21, s13, 7
	s_add_i32 s20, s20, s21
	v_lshlrev_b32_e32 v133, 10, v131
	v_lshl_add_u32 v133, v132, 4, v133
	v_add_u32_e32 v133, s20, v133
	s_lshl_b32 s20, s12, 16
	s_sub_i32 s20, 0x13e00, s20
	s_add_i32 s20, s20, s21
	v_lshlrev_b32_e32 v134, 10, v131
	v_sub_u32_e32 v134, s20, v134
	v_lshl_add_u32 v134, v132, 4, v134
	s_cmp_gt_i32 s1, 1
	s_cbranch_scc1 .Lcarry_setup_done
	s_lshl_b32 s12, s70, 7
	s_lshl_b32 s23, s1, 6
	s_add_i32 s12, s12, s2
	s_add_i32 s12, s12, s23
	v_lshl_or_b32 v136, s12, 6, v130
	v_mov_b32_e32 v137, 0
	v_readlane_b32 s28, v254, 22
	v_readlane_b32 s29, v254, 23
	s_nop 1
	v_lshl_add_u64 v[136:137], v[136:137], 3, s[28:29]
	global_load_dwordx2 v[138:139], v[136:137], off
	s_lshl_b32 s23, s1, 9
	v_lshl_add_u32 v140, v130, 2, s23
	s_mul_i32 s26, s1, 0x5fb00
	v_lshl_add_u32 v141, v130, 1, s26
	s_mul_i32 s36, s1, 0xfffff400
	s_add_i32 s36, s36, 0x600
	v_readlane_b32 s34, v254, 28
	v_readlane_b32 s35, v254, 29
	v_mov_b32_e32 v142, 0
	v_mov_b32_e32 v143, 0
.Lcarry_setup_done:
	ds_write_b128 v133, v[126:129] offset:0
	ds_write_b128 v133, v[122:125] offset:64
	ds_write_b128 v133, v[118:121] offset:16384
	ds_write_b128 v133, v[114:117] offset:16448
	ds_write_b128 v133, v[106:109] offset:32768
	ds_write_b128 v133, v[98:101] offset:32832
	ds_write_b128 v133, v[90:93] offset:49152
	ds_write_b128 v133, v[82:85] offset:49216
	ds_write_b128 v134, v[46:49] offset:49152
	ds_write_b128 v134, v[42:45] offset:49216
	ds_write_b128 v134, v[30:33] offset:32768
	ds_write_b128 v134, v[26:29] offset:32832
	ds_write_b128 v134, v[14:17] offset:16384
	ds_write_b128 v134, v[10:13] offset:16448
	ds_write_b128 v134, v[6:9] offset:0
	ds_write_b128 v134, v[2:5] offset:64
	s_waitcnt vmcnt(0) lgkmcnt(0)
	s_barrier
	s_cmp_gt_i32 s1, 1
	s_cbranch_scc1 .Lcarry_skip0
	v_mov_b32_e32 v150, v140
	ds_read2st64_b32 v[170:171], v150 offset0:0 offset1:1
	ds_read2st64_b32 v[172:173], v150 offset0:4 offset1:5
	ds_read2st64_b32 v[174:175], v150 offset0:8 offset1:9
	ds_read2st64_b32 v[176:177], v150 offset0:12 offset1:13
	ds_read2st64_b32 v[178:179], v150 offset0:16 offset1:17
	ds_read2st64_b32 v[180:181], v150 offset0:20 offset1:21
	ds_read2st64_b32 v[182:183], v150 offset0:24 offset1:25
	ds_read2st64_b32 v[184:185], v150 offset0:28 offset1:29
	s_mov_b32 s12, 0
; __device__ __forceinline__ unsigned cvt_pk_bf16(float lo, float hi) { unsigned r; asm volatile("v_cvt_pk_bf16_f32 %0, %1, %2" : "=v"(r) : "v"(lo), "v"(hi)); return r; }
; __device__ __forceinline__ void s5_carry2(const Params& P, int j, int g) {
;     ...
;         for (int s0 = 0; s0 < 256; s0 += 8) {
;             if (s0 + 8 < 256) {
; #pragma unroll
;                 for (int u = 0; u < 8; ++u) { const int n = dir ? (255 - (s0 + 8 + u)) : (s0 + 8 + u); nzr[u] = zp[(size_t)n * 256]; nzi[u] = zp[(size_t)n * 256 + 64]; }
;             }
; #pragma unroll
;             for (int u = 0; u < 8; ++u) { const int n = dir ? (255 - (s0 + u)) : (s0 + u);
;                 up[(size_t)n * 768] = (bf16_t)(cvt_pk_bf16(cr, 0.f) & 0xffffu); up[(size_t)n * 768 + 64] = (bf16_t)(cvt_pk_bf16(cim, 0.f) & 0xffffu);
;                 const float nr = ar * cr - ai * cim + zr[u], ni = ar * cim + ai * cr + zi[u]; cr = nr; cim = ni; }
; #pragma unroll
;             for (int u = 0; u < 8; ++u) { zr[u] = nzr[u]; zi[u] = nzi[u]; }
;         }
.Lcarry_loop0:
	s_waitcnt lgkmcnt(0)
	ds_read2st64_b32 v[186:187], v150 offset0:32 offset1:33
	ds_read2st64_b32 v[188:189], v150 offset0:36 offset1:37
	ds_read2st64_b32 v[190:191], v150 offset0:40 offset1:41
	ds_read2st64_b32 v[192:193], v150 offset0:44 offset1:45
	ds_read2st64_b32 v[194:195], v150 offset0:48 offset1:49
	ds_read2st64_b32 v[196:197], v150 offset0:52 offset1:53
	ds_read2st64_b32 v[198:199], v150 offset0:56 offset1:57
	ds_read2st64_b32 v[210:211], v150 offset0:60 offset1:61
	v_cvt_pk_bf16_f32 v144, v142, v143
	global_store_short v141, v144, s[34:35]
	global_store_short_d16_hi v141, v144, s[34:35] offset:128
	v_fma_f32 v146, v138, v142, v170
	v_fma_f32 v147, v138, v143, v171
	v_add_u32_e32 v141, s36, v141
	v_fma_f32 v148, -v139, v143, v146
	v_fma_f32 v149, v139, v142, v147
	v_cvt_pk_bf16_f32 v145, v148, v149
	global_store_short v141, v145, s[34:35]
	global_store_short_d16_hi v141, v145, s[34:35] offset:128
	v_fma_f32 v146, v138, v148, v172
	v_fma_f32 v147, v138, v149, v173
	v_add_u32_e32 v141, s36, v141
	v_fma_f32 v142, -v139, v149, v146
	v_fma_f32 v143, v139, v148, v147
	v_cvt_pk_bf16_f32 v144, v142, v143
	global_store_short v141, v144, s[34:35]
	global_store_short_d16_hi v141, v144, s[34:35] offset:128
	v_fma_f32 v146, v138, v142, v174
	v_fma_f32 v147, v138, v143, v175
	v_add_u32_e32 v141, s36, v141
	v_fma_f32 v148, -v139, v143, v146
	v_fma_f32 v149, v139, v142, v147
	v_cvt_pk_bf16_f32 v145, v148, v149
	global_store_short v141, v145, s[34:35]
	global_store_short_d16_hi v141, v145, s[34:35] offset:128
	v_fma_f32 v146, v138, v148, v176
	v_fma_f32 v147, v138, v149, v177
	v_add_u32_e32 v141, s36, v141
	v_fma_f32 v142, -v139, v149, v146
	v_fma_f32 v143, v139, v148, v147
	v_cvt_pk_bf16_f32 v144, v142, v143
	global_store_short v141, v144, s[34:35]
	global_store_short_d16_hi v141, v144, s[34:35] offset:128
	v_fma_f32 v146, v138, v142, v178
	v_fma_f32 v147, v138, v143, v179
	v_add_u32_e32 v141, s36, v141
	v_fma_f32 v148, -v139, v143, v146
	v_fma_f32 v149, v139, v142, v147
	v_cvt_pk_bf16_f32 v145, v148, v149
	global_store_short v141, v145, s[34:35]
	global_store_short_d16_hi v141, v145, s[34:35] offset:128
	v_fma_f32 v146, v138, v148, v180
	v_fma_f32 v147, v138, v149, v181
	v_add_u32_e32 v141, s36, v141
	v_fma_f32 v142, -v139, v149, v146
	v_fma_f32 v143, v139, v148, v147
	v_cvt_pk_bf16_f32 v144, v142, v143
	global_store_short v141, v144, s[34:35]
	global_store_short_d16_hi v141, v144, s[34:35] offset:128
	v_fma_f32 v146, v138, v142, v182
	v_fma_f32 v147, v138, v143, v183
	v_add_u32_e32 v141, s36, v141
	v_fma_f32 v148, -v139, v143, v146
	v_fma_f32 v149, v139, v142, v147
	v_cvt_pk_bf16_f32 v145, v148, v149
	global_store_short v141, v145, s[34:35]
	global_store_short_d16_hi v141, v145, s[34:35] offset:128
	v_fma_f32 v146, v138, v148, v184
	v_fma_f32 v147, v138, v149, v185
	v_add_u32_e32 v141, s36, v141
	v_fma_f32 v142, -v139, v149, v146
	v_fma_f32 v143, v139, v148, v147
	s_waitcnt lgkmcnt(0)
	ds_read2st64_b32 v[170:171], v150 offset0:64 offset1:65
	ds_read2st64_b32 v[172:173], v150 offset0:68 offset1:69
	ds_read2st64_b32 v[174:175], v150 offset0:72 offset1:73
	ds_read2st64_b32 v[176:177], v150 offset0:76 offset1:77
	ds_read2st64_b32 v[178:179], v150 offset0:80 offset1:81
	ds_read2st64_b32 v[180:181], v150 offset0:84 offset1:85
	ds_read2st64_b32 v[182:183], v150 offset0:88 offset1:89
	ds_read2st64_b32 v[184:185], v150 offset0:92 offset1:93
	v_cvt_pk_bf16_f32 v144, v142, v143
	global_store_short v141, v144, s[34:35]
	global_store_short_d16_hi v141, v144, s[34:35] offset:128
	v_fma_f32 v146, v138, v142, v186
	v_fma_f32 v147, v138, v143, v187
	v_add_u32_e32 v141, s36, v141
	v_fma_f32 v148, -v139, v143, v146
	v_fma_f32 v149, v139, v142, v147
	v_cvt_pk_bf16_f32 v145, v148, v149
	global_store_short v141, v145, s[34:35]
	global_store_short_d16_hi v141, v145, s[34:35] offset:128
	v_fma_f32 v146, v138, v148, v188
	v_fma_f32 v147, v138, v149, v189
	v_add_u32_e32 v141, s36, v141
	v_fma_f32 v142, -v139, v149, v146
	v_fma_f32 v143, v139, v148, v147
	v_cvt_pk_bf16_f32 v144, v142, v143
	global_store_short v141, v144, s[34:35]
	global_store_short_d16_hi v141, v144, s[34:35] offset:128
	v_fma_f32 v146, v138, v142, v190
	v_fma_f32 v147, v138, v143, v191
	v_add_u32_e32 v141, s36, v141
	v_fma_f32 v148, -v139, v143, v146
	v_fma_f32 v149, v139, v142, v147
	v_cvt_pk_bf16_f32 v145, v148, v149
	global_store_short v141, v145, s[34:35]
	global_store_short_d16_hi v141, v145, s[34:35] offset:128
	v_fma_f32 v146, v138, v148, v192
	v_fma_f32 v147, v138, v149, v193
	v_add_u32_e32 v141, s36, v141
	v_fma_f32 v142, -v139, v149, v146
	v_fma_f32 v143, v139, v148, v147
	v_cvt_pk_bf16_f32 v144, v142, v143
	global_store_short v141, v144, s[34:35]
	global_store_short_d16_hi v141, v144, s[34:35] offset:128
	v_fma_f32 v146, v138, v142, v194
	v_fma_f32 v147, v138, v143, v195
	v_add_u32_e32 v141, s36, v141
	v_fma_f32 v148, -v139, v143, v146
	v_fma_f32 v149, v139, v142, v147
	v_cvt_pk_bf16_f32 v145, v148, v149
	global_store_short v141, v145, s[34:35]
	global_store_short_d16_hi v141, v145, s[34:35] offset:128
	v_fma_f32 v146, v138, v148, v196
	v_fma_f32 v147, v138, v149, v197
	v_add_u32_e32 v141, s36, v141
	v_fma_f32 v142, -v139, v149, v146
	v_fma_f32 v143, v139, v148, v147
	v_cvt_pk_bf16_f32 v144, v142, v143
	global_store_short v141, v144, s[34:35]
	global_store_short_d16_hi v141, v144, s[34:35] offset:128
	v_fma_f32 v146, v138, v142, v198
	v_fma_f32 v147, v138, v143, v199
	v_add_u32_e32 v141, s36, v141
	v_fma_f32 v148, -v139, v143, v146
	v_fma_f32 v149, v139, v142, v147
	v_cvt_pk_bf16_f32 v145, v148, v149
	global_store_short v141, v145, s[34:35]
	global_store_short_d16_hi v141, v145, s[34:35] offset:128
	v_fma_f32 v146, v138, v148, v210
	v_fma_f32 v147, v138, v149, v211
	v_add_u32_e32 v141, s36, v141
	v_fma_f32 v142, -v139, v149, v146
	v_fma_f32 v143, v139, v148, v147
	v_add_u32_e32 v150, 0x4000, v150
	s_add_i32 s12, s12, 1
	s_cmp_lt_u32 s12, 8
	s_cbranch_scc1 .Lcarry_loop0
	s_waitcnt lgkmcnt(0)
; #define LAS __attribute__((address_space(3)))
;     __device__ __forceinline__ void operator()(const f32x4 (&acc)[2][2][4][2], const Unit& u, int ui, const LAS float* rtab, int wr, int wc, int fr, int fq) const {
;         const int row0 = u.pm * BM + wr * 64 + fr, col0 = wc * 32 + 4 * fq;
; #pragma unroll
;         for (int ai = 0; ai < 2; ++ai)
; #pragma unroll
;             for (int m = 0; m < 4; ++m) { float* rowp = Z + (size_t)(row0 + ai * HALF + m * 16) * 256 + col0;
; #pragma unroll
;                 for (int bj = 0; bj < 2; ++bj)
; #pragma unroll
;                     for (int n = 0; n < 2; ++n) *(f32x4*)(rowp + bj * HALF + n * 16) = acc[ai][bj][m][n]; }
;     }
; __device__ __forceinline__ void s5_carry2(const Params& P, int j, int g) {
;     ...
;         for (int s0 = 0; s0 < 256; s0 += 8) {
;             if (s0 + 8 < 256) {
; #pragma unroll
;                 for (int u = 0; u < 8; ++u) { const int n = dir ? (255 - (s0 + 8 + u)) : (s0 + 8 + u); nzr[u] = zp[(size_t)n * 256]; nzi[u] = zp[(size_t)n * 256 + 64]; }
;             }
; #pragma unroll
.Lcarry_skip0:
	s_barrier
	ds_write_b128 v133, v[62:65] offset:0
	ds_write_b128 v133, v[58:61] offset:64
	ds_write_b128 v133, v[54:57] offset:16384
	ds_write_b128 v133, v[50:53] offset:16448
	ds_write_b128 v133, v[38:41] offset:32768
	ds_write_b128 v133, v[34:37] offset:32832
	ds_write_b128 v133, v[22:25] offset:49152
	ds_write_b128 v133, v[18:21] offset:49216
	ds_write_b128 v134, v[110:113] offset:49152
	ds_write_b128 v134, v[102:105] offset:49216
	ds_write_b128 v134, v[94:97] offset:32768
	ds_write_b128 v134, v[86:89] offset:32832
	ds_write_b128 v134, v[78:81] offset:16384
	ds_write_b128 v134, v[74:77] offset:16448
	ds_write_b128 v134, v[70:73] offset:0
	ds_write_b128 v134, v[66:69] offset:64
	s_waitcnt lgkmcnt(0)
	s_barrier
	s_cmp_gt_i32 s1, 1
	s_cbranch_scc1 .Lcarry_skip1
	v_mov_b32_e32 v150, v140
	ds_read2st64_b32 v[170:171], v150 offset0:0 offset1:1
	ds_read2st64_b32 v[172:173], v150 offset0:4 offset1:5
	ds_read2st64_b32 v[174:175], v150 offset0:8 offset1:9
	ds_read2st64_b32 v[176:177], v150 offset0:12 offset1:13
	ds_read2st64_b32 v[178:179], v150 offset0:16 offset1:17
	ds_read2st64_b32 v[180:181], v150 offset0:20 offset1:21
	ds_read2st64_b32 v[182:183], v150 offset0:24 offset1:25
	ds_read2st64_b32 v[184:185], v150 offset0:28 offset1:29
	s_mov_b32 s12, 0

; template <class Epi, class Sched>
; __device__ __forceinline__ void gemm_phase(LAS unsigned char* lds, const Gemm g, const Sched& S, const Epi& E) {
;     ...
;     const int wid = __builtin_amdgcn_readfirstlane(tid >> 6), lane = tid & 63, wr = wid >> 2, wc = wid & 3, fr = lane & 15, fq = lane >> 4;
;     const int K = g.K, nt = K / BK;
;     unsigned voffA[2], voffB[2];
; #pragma unroll
;     for (int i = 0; i < 2; ++i) { int R, C; stage_rc(tid * 16 + i * 8192, R, C); const int Rb = Epi::PERM ? ((R & ~31) + perm32(R & 31)) : R;
;         voffA[i] = (unsigned)(R * g.lda + C) * 2u; voffB[i] = (unsigned)(Rb * g.ldb + C) * 2u; }
;     const size_t kstep = (size_t)(BK * 2);
;     const size_t hstepA = (size_t)HALF * g.lda * 2, hstepB = (size_t)HALF * g.ldb * 2;
;     const size_t tstepA = 2 * hstepA, tstepB = 2 * hstepB;
;     const unsigned ldsw = (unsigned)wid * 1024u;
;     const int aoff = lds_byte(wr * 64 + fr, fq * 8), boff = lds_byte(wc * 32 + fr, fq * 8);
;     ...
;     Unit cur, nxt; int ui = 0;
;     if (!S.next(0, cur)) return;
;     f32x4 acc[2][2][4][2];
; #pragma unroll
;     for (int a = 0; a < 2; ++a)
; #pragma unroll
;         for (int b = 0; b < 2; ++b)
; #pragma unroll
;             for (int m = 0; m < 4; ++m)
; #pragma unroll
;                 for (int n = 0; n < 2; ++n) acc[a][b][m][n] = (f32x4){0.f, 0.f, 0.f, 0.f};
;     bf16x8 At[4][2], B0[2][2], B1[2][2];
;     const char* cA = (const char*)g.A + (size_t)cur.pm * tstepA; const char* cB = (const char*)g.Bt + (size_t)cur.pn * tstepB;
;     PG8_STAGE(PG8_SB(0, 0), cB, voffB); PG8_STAGE(PG8_SA(0, 0), cA, voffA); PG8_STAGE(PG8_SB(0, 1), cB + hstepB, voffB); PG8_STAGE(PG8_SA(0, 1), cA + hstepA, voffA);
; __global__ void __launch_bounds__(NTHR) hybrid_encoder_fwd(Params P) {
;     ...
;                     __builtin_amdgcn_fence(__ATOMIC_ACQUIRE, "agent"); asm volatile("s_waitcnt vmcnt(0)" ::: "memory"); __syncthreads();
;                     Gemm g3; g3.A = U2; g3.Bt = (const bf16_t*)(ws + WS_B3 + j * SZ_B3); g3.lda = 768; g3.ldb = 768; g3.K = 768;
;                     ListOrder S3; S3.total = 128; S3.G = 64; S3.c = bid; S3.mode = 2;
;                     EpiP3 E3; E3.Y = Y;
;                     gemm_phase<EpiP3, ListOrder>(lds, g3, S3, E3);
.Lcarry_skip1:
	s_barrier
.LBB0_591:
	v_mov_b32_e32 v6, v200
	s_barrier
	s_waitcnt vmcnt(0)
	s_barrier
	s_waitcnt vmcnt(0)
	buffer_inv sc1
	s_waitcnt vmcnt(0)
	s_barrier
	s_mul_i32 s1, s70, 0x3000000
	v_ashrrev_i32_e32 v2, 31, v6
	v_lshrrev_b32_e32 v2, 26, v2
	v_add_u32_e32 v2, v6, v2
	v_ashrrev_i32_e32 v7, 6, v2
	v_bfe_i32 v2, v6, 27, 1
	v_lshlrev_b32_e32 v1, 4, v6
	v_lshrrev_b32_e32 v2, 22, v2
	v_add_u32_e32 v2, v1, v2
	v_and_b32_e32 v2, 0xfffffc00, v2
	v_sub_u32_e32 v2, v1, v2
	v_lshrrev_b32_e32 v3, 4, v2
	v_bitop3_b32 v2, v3, v2, 32 bitop3:0x6c
	v_ashrrev_i32_e32 v4, 31, v2
	v_lshrrev_b32_e32 v4, 26, v4
	v_lshlrev_b32_e32 v3, 3, v7
	v_add_u32_e32 v4, v2, v4
	v_readlane_b32 s12, v254, 30
	v_and_b32_e32 v3, -16, v3
	v_ashrrev_i32_e32 v9, 6, v4
	v_and_b32_e32 v4, 0xc0, v4
	s_mul_hi_u32 s0, s70, 0x3000000
	s_add_u32 s21, s12, s1
	v_readlane_b32 s1, v254, 31
	v_add_u32_e32 v3, v9, v3
	v_lshlrev_b32_e32 v5, 5, v7
	v_sub_u32_e32 v2, v2, v4
	s_addc_u32 s20, s1, s0
	v_and_b32_e32 v8, 32, v5
	v_ashrrev_i16_sdwa v2, v204, sext(v2) dst_sel:DWORD dst_unused:UNUSED_PAD src0_sel:DWORD src1_sel:BYTE_0
	v_lshlrev_b32_e32 v4, 1, v3
	v_lshrrev_b32_e32 v5, 2, v3
	v_and_b32_e32 v11, 3, v9
	s_mov_b32 s1, 0xffffe0
	v_bfe_i32 v10, v2, 0, 16
	v_and_b32_e32 v4, 24, v4
	v_and_b32_e32 v5, 4, v5
	v_and_or_b32 v11, v3, s1, v11
	s_movk_i32 s0, 0x300
	v_add_u32_e32 v2, v8, v10
	v_or3_b32 v4, v11, v5, v4
	v_mul_lo_u32 v3, v3, s0
	v_add_lshl_u32 v130, v2, v3, 1
	v_mul_u32_u24_e32 v3, 0x300, v4
	v_add_u32_e32 v1, 0x2000, v1
	v_add_lshl_u32 v132, v3, v2, 1
	v_ashrrev_i32_e32 v2, 31, v1
	v_lshrrev_b32_e32 v2, 22, v2
	v_add_u32_e32 v2, v1, v2
	v_ashrrev_i32_e32 v11, 10, v2
	v_mul_i32_i24_e32 v2, 0x400, v11
	v_sub_u32_e32 v1, v1, v2
	v_lshrrev_b32_e32 v2, 4, v1
	v_bitop3_b32 v1, v2, v1, 32 bitop3:0x6c
	v_ashrrev_i32_e32 v3, 31, v1
	v_lshrrev_b32_e32 v3, 26, v3
	v_lshlrev_b32_e32 v2, 3, v11
	v_add_u32_e32 v3, v1, v3
	v_readfirstlane_b32 s12, v6
	v_and_b32_e32 v2, -16, v2
	v_ashrrev_i32_e32 v13, 6, v3
	v_and_b32_e32 v3, 0xc0, v3
	v_add_u32_e32 v2, v13, v2
	v_lshlrev_b32_e32 v4, 5, v11
	v_sub_u32_e32 v1, v1, v3
	v_and_b32_e32 v5, 3, v13
	s_ashr_i32 s28, s12, 6
	s_ashr_i32 s26, s12, 8
	v_and_b32_e32 v12, 32, v4
	v_ashrrev_i16_sdwa v1, v204, sext(v1) dst_sel:DWORD dst_unused:UNUSED_PAD src0_sel:DWORD src1_sel:BYTE_0
	v_lshlrev_b32_e32 v3, 1, v2
	v_lshrrev_b32_e32 v4, 2, v2
	v_and_or_b32 v5, v2, s1, v5
	v_mul_lo_u32 v2, v2, s0
	s_lshl_b32 s13, s28, 10
	s_mul_i32 s0, s2, 0xc0000
	v_readlane_b32 s1, v252, 17
	v_bfe_i32 v14, v1, 0, 16
	v_and_b32_e32 v3, 24, v3
	v_and_b32_e32 v4, 4, v4
	s_add_u32 s0, s21, s0
	s_mul_hi_i32 s1, s1, 0x60000
	v_add_u32_e32 v1, v12, v14
	v_or3_b32 v3, v5, v4, v3
	s_addc_u32 s1, s20, s1
	s_add_i32 s34, s13, 0
	v_add_lshl_u32 v134, v1, v2, 1
	v_mul_u32_u24_e32 v2, 0x300, v3
	s_add_i32 m0, s34, 0x10000
	v_add_lshl_u32 v136, v2, v1, 1
	global_load_lds_dwordx4 v132, s[0:1]
	s_add_i32 m0, s34, 0x12000
	v_readlane_b32 s36, v254, 13
	global_load_lds_dwordx4 v136, s[0:1]
	s_mov_b32 m0, s34
	v_readlane_b32 s37, v254, 14
	s_add_i32 s35, s34, 0x2000
	v_mov_b32_e32 v133, v0
	v_mov_b32_e32 v137, v0
	v_lshl_add_u64 v[2:3], s[0:1], 0, v[132:133]
	v_lshl_add_u64 v[4:5], s[0:1], 0, v[136:137]
	global_load_lds_dwordx4 v130, s[36:37]
	s_mov_b32 m0, s35
	s_nop 0
	global_load_lds_dwordx4 v134, s[36:37]
	s_add_u32 s36, s0, 0x30000
	s_addc_u32 s37, s1, 0
	s_add_i32 m0, s34, 0x14000
	s_add_i32 s48, s34, 0x4000
	global_load_lds_dwordx4 v132, s[36:37]
	s_add_i32 m0, s34, 0x16000
	s_add_i32 s49, s34, 0x6000
	global_load_lds_dwordx4 v136, s[36:37]
	v_readlane_b32 s36, v254, 15
	s_mov_b32 m0, s48
	v_readlane_b32 s37, v254, 16
	s_cmp_lg_u32 s26, 1
	s_nop 3
	global_load_lds_dwordx4 v130, s[36:37]
	s_mov_b32 m0, s49
	s_nop 0
	global_load_lds_dwordx4 v134, s[36:37]
	s_cbranch_scc1 .LBB0_593
	s_barrier
